# EpiGU: leading half runs the first four row blocks of its epilogue before the aligning barrier (instead of idling there)
# baseline (speedup 1.0000x reference)
; #define LAS __attribute__((address_space(3)))
; __device__ __forceinline__ float siluf_(float x) { return x * sigmoidf_(x); }
; __device__ __forceinline__ void rows_rstd(LAS unsigned char* sl, int rl0, int fq, float (&rs)[8]) {
;     f32x4 v[8];
; #pragma unroll
;     for (int i = 0; i < 8; ++i) v[i] = *(const LAS f32x4*)(sl + (rl0 + (i >> 2) * 128 + (i & 3) * 16) * 64 + fq * 16);
; #pragma unroll
;     for (int i = 0; i < 8; ++i) { float s = (v[i].x + v[i].y) + (v[i].z + v[i].w); s += __shfl_xor(s, 16); s += __shfl_xor(s, 32); rs[i] = rsqrtf(s * (1.0f / DM) + EPS); }
; }
;     __device__ __forceinline__ void operator()(const f32x4 (&acc)[2][2][4][2], const pg8::Unit& u, int wr, int wc, int fr, int fq) const {
;         const int row0 = u.pm * 256 + wr * 64 + fr, col0 = u.pn * 128 + wc * 32 + 8 * fq;
;         float rs[8]; rows_rstd(sl, wr * 64 + fr, fq, rs);
; #pragma unroll
;         for (int ai = 0; ai < 2; ++ai)
; #pragma unroll
;             for (int m = 0; m < 4; ++m) {
;                 const int row = row0 + ai * 128 + m * 16; const float r = rs[ai * 4 + m];
;                 float h[8];
; #pragma unroll
;                 for (int n = 0; n < 2; ++n)
; #pragma unroll
;                     for (int j = 0; j < 4; ++j) { const float g = acc[ai][0][m][n][j] * r, up = acc[ai][1][m][n][j] * r; h[n * 4 + j] = siluf_(g) * up; }
.LBB0_1650:
	v_xor_b32_e32 v130, 16, v175
	v_xor_b32_e32 v131, 32, v175
	ds_read_b128 v[200:203], v198
	ds_read_b128 v[204:207], v198 offset:1024
	ds_read_b128 v[208:211], v198 offset:2048
	ds_read_b128 v[212:215], v198 offset:3072
	ds_read_b128 v[216:219], v198 offset:8192
	ds_read_b128 v[220:223], v198 offset:9216
	ds_read_b128 v[224:227], v198 offset:10240
	ds_read_b128 v[228:231], v198 offset:11264
	v_lshlrev_b32_e32 v130, 2, v130
	v_lshlrev_b32_e32 v131, 2, v131
	v_mov_b32_e32 v134, 0xbfb8aa3b
	v_mov_b32_e32 v135, 0x3a800000
	v_add_u32_e32 v132, s45, v163
	v_mul_u32_u24_e32 v132, 0x1600, v132
	v_lshl_or_b32 v133, s38, 7, v171
	v_lshl_add_u32 v132, v133, 1, v132
	s_waitcnt lgkmcnt(0)
	v_add_f32_e32 v232, v200, v201
	v_add_f32_e32 v233, v204, v205
	v_add_f32_e32 v234, v208, v209
	v_add_f32_e32 v235, v212, v213
	v_add_f32_e32 v236, v216, v217
	v_add_f32_e32 v237, v220, v221
	v_add_f32_e32 v238, v224, v225
	v_add_f32_e32 v239, v228, v229
	v_add_f32_e32 v240, v202, v203
	v_add_f32_e32 v241, v206, v207
	v_add_f32_e32 v242, v210, v211
	v_add_f32_e32 v243, v214, v215
	v_add_f32_e32 v244, v218, v219
	v_add_f32_e32 v245, v222, v223
	v_add_f32_e32 v246, v226, v227
	v_add_f32_e32 v247, v230, v231
	v_add_f32_e32 v232, v232, v240
	v_add_f32_e32 v233, v233, v241
	v_add_f32_e32 v234, v234, v242
	v_add_f32_e32 v235, v235, v243
	v_add_f32_e32 v236, v236, v244
	v_add_f32_e32 v237, v237, v245
	v_add_f32_e32 v238, v238, v246
	v_add_f32_e32 v239, v239, v247
	ds_bpermute_b32 v240, v130, v232
	ds_bpermute_b32 v241, v130, v233
	ds_bpermute_b32 v242, v130, v234
	ds_bpermute_b32 v243, v130, v235
	ds_bpermute_b32 v244, v130, v236
	ds_bpermute_b32 v245, v130, v237
	ds_bpermute_b32 v246, v130, v238
	ds_bpermute_b32 v247, v130, v239
	s_waitcnt lgkmcnt(0)
	v_add_f32_e32 v232, v232, v240
	v_add_f32_e32 v233, v233, v241
	v_add_f32_e32 v234, v234, v242
	v_add_f32_e32 v235, v235, v243
	v_add_f32_e32 v236, v236, v244
	v_add_f32_e32 v237, v237, v245
	v_add_f32_e32 v238, v238, v246
	v_add_f32_e32 v239, v239, v247
	ds_bpermute_b32 v240, v131, v232
	ds_bpermute_b32 v241, v131, v233
	ds_bpermute_b32 v242, v131, v234
	ds_bpermute_b32 v243, v131, v235
	ds_bpermute_b32 v244, v131, v236
	ds_bpermute_b32 v245, v131, v237
	ds_bpermute_b32 v246, v131, v238
	ds_bpermute_b32 v247, v131, v239
	s_waitcnt lgkmcnt(0)
	v_add_f32_e32 v232, v232, v240
	v_add_f32_e32 v233, v233, v241
	v_add_f32_e32 v234, v234, v242
	v_add_f32_e32 v235, v235, v243
	v_add_f32_e32 v236, v236, v244
	v_add_f32_e32 v237, v237, v245
	v_add_f32_e32 v238, v238, v246
	v_add_f32_e32 v239, v239, v247
	v_fmaak_f32 v216, v135, v232, 0x358637bd
	v_fmaak_f32 v218, v135, v233, 0x358637bd
	v_fmaak_f32 v220, v135, v234, 0x358637bd
	v_fmaak_f32 v222, v135, v235, 0x358637bd
	v_fmaak_f32 v224, v135, v236, 0x358637bd
	v_fmaak_f32 v226, v135, v237, 0x358637bd
	v_fmaak_f32 v228, v135, v238, 0x358637bd
	v_fmaak_f32 v230, v135, v239, 0x358637bd
	v_rsq_f32_e32 v200, v216
	v_rsq_f32_e32 v202, v218
	v_rsq_f32_e32 v204, v220
	v_rsq_f32_e32 v206, v222
	v_rsq_f32_e32 v208, v224
	v_rsq_f32_e32 v210, v226
	v_rsq_f32_e32 v212, v228
	v_rsq_f32_e32 v214, v230
	v_mul_f32_e32 v200, v134, v200
	v_mul_f32_e32 v202, v134, v202
	v_mul_f32_e32 v204, v134, v204
	v_mul_f32_e32 v206, v134, v206
	v_mul_f32_e32 v208, v134, v208
	v_mul_f32_e32 v210, v134, v210
	v_mul_f32_e32 v212, v134, v212
	v_mul_f32_e32 v214, v134, v214
	v_pk_mul_f32 v[120:121], v[124:125], v[120:121]
	v_pk_mul_f32 v[122:123], v[126:127], v[122:123]
	v_pk_mul_f32 v[112:113], v[116:117], v[112:113]
	v_pk_mul_f32 v[114:115], v[118:119], v[114:115]
	v_pk_mul_f32 v[104:105], v[108:109], v[104:105]
	v_pk_mul_f32 v[106:107], v[110:111], v[106:107]
	v_pk_mul_f32 v[96:97], v[100:101], v[96:97]
	v_pk_mul_f32 v[98:99], v[102:103], v[98:99]
	v_pk_mul_f32 v[124:125], v[124:125], v[200:201] op_sel_hi:[1,0]
	v_pk_mul_f32 v[126:127], v[126:127], v[200:201] op_sel_hi:[1,0]
	v_pk_mul_f32 v[116:117], v[116:117], v[200:201] op_sel_hi:[1,0]
	v_pk_mul_f32 v[118:119], v[118:119], v[200:201] op_sel_hi:[1,0]
	v_pk_mul_f32 v[108:109], v[108:109], v[202:203] op_sel_hi:[1,0]
	v_pk_mul_f32 v[110:111], v[110:111], v[202:203] op_sel_hi:[1,0]
	v_pk_mul_f32 v[100:101], v[100:101], v[202:203] op_sel_hi:[1,0]
	v_pk_mul_f32 v[102:103], v[102:103], v[202:203] op_sel_hi:[1,0]
	v_exp_f32_e32 v124, v124
	v_exp_f32_e32 v125, v125
	v_exp_f32_e32 v126, v126
	v_exp_f32_e32 v127, v127
	v_exp_f32_e32 v116, v116
	v_exp_f32_e32 v117, v117
	v_exp_f32_e32 v118, v118
	v_exp_f32_e32 v119, v119
	v_exp_f32_e32 v108, v108
	v_exp_f32_e32 v109, v109
	v_exp_f32_e32 v110, v110
	v_exp_f32_e32 v111, v111
	v_exp_f32_e32 v100, v100
	v_exp_f32_e32 v101, v101
	v_exp_f32_e32 v102, v102
	v_exp_f32_e32 v103, v103
	v_pk_fma_f32 v[124:125], v[124:125], v[216:217], v[216:217] op_sel_hi:[1,0,0]
	v_pk_fma_f32 v[126:127], v[126:127], v[216:217], v[216:217] op_sel_hi:[1,0,0]
	v_pk_fma_f32 v[116:117], v[116:117], v[216:217], v[216:217] op_sel_hi:[1,0,0]
	v_pk_fma_f32 v[118:119], v[118:119], v[216:217], v[216:217] op_sel_hi:[1,0,0]
	v_pk_fma_f32 v[108:109], v[108:109], v[218:219], v[218:219] op_sel_hi:[1,0,0]
	v_pk_fma_f32 v[110:111], v[110:111], v[218:219], v[218:219] op_sel_hi:[1,0,0]
	v_pk_fma_f32 v[100:101], v[100:101], v[218:219], v[218:219] op_sel_hi:[1,0,0]
	v_pk_fma_f32 v[102:103], v[102:103], v[218:219], v[218:219] op_sel_hi:[1,0,0]
	v_rcp_f32_e32 v124, v124
	v_rcp_f32_e32 v125, v125
	v_rcp_f32_e32 v126, v126
	v_rcp_f32_e32 v127, v127
	v_rcp_f32_e32 v116, v116
	v_rcp_f32_e32 v117, v117
	v_rcp_f32_e32 v118, v118
	v_rcp_f32_e32 v119, v119
	v_rcp_f32_e32 v108, v108
	v_rcp_f32_e32 v109, v109
	v_rcp_f32_e32 v110, v110
	v_rcp_f32_e32 v111, v111
; #define PG8_BAR __builtin_amdgcn_s_barrier()
; __device__ __forceinline__ unsigned pk2(float lo, float hi) { return pg8::cvt_pk_bf16(lo, hi); }
; __device__ __forceinline__ float siluf_(float x) { return x * sigmoidf_(x); }
; template <class Epi, class Sched, bool ALIGN_EPI = false, bool SP2 = false>
; __device__ __forceinline__ void gemm_phase(PG8_LAS unsigned char* lds, const Gemm g, const Sched& S, const Epi& E) {
;     ...
;         if constexpr (ALIGN_EPI) { if (wr == 0) PG8_BAR; }
;     __device__ __forceinline__ void operator()(const f32x4 (&acc)[2][2][4][2], const pg8::Unit& u, int wr, int wc, int fr, int fq) const {
;     ...
;         for (int ai = 0; ai < 2; ++ai)
; #pragma unroll
;             for (int m = 0; m < 4; ++m) {
;                 const int row = row0 + ai * 128 + m * 16; const float r = rs[ai * 4 + m];
;                 float h[8];
; #pragma unroll
;                 for (int n = 0; n < 2; ++n)
; #pragma unroll
;                     for (int j = 0; j < 4; ++j) { const float g = acc[ai][0][m][n][j] * r, up = acc[ai][1][m][n][j] * r; h[n * 4 + j] = siluf_(g) * up; }
;                 u32x4 w; w.x = pk2(h[0], h[1]); w.y = pk2(h[2], h[3]); w.z = pk2(h[4], h[5]); w.w = pk2(h[6], h[7]);
;                 *(u32x4*)(H + (size_t)row * FF + col0) = w;
	v_rcp_f32_e32 v100, v100
	v_rcp_f32_e32 v101, v101
	v_rcp_f32_e32 v102, v102
	v_rcp_f32_e32 v103, v103
	v_pk_mul_f32 v[120:121], v[120:121], v[124:125]
	v_pk_mul_f32 v[122:123], v[122:123], v[126:127]
	v_pk_mul_f32 v[112:113], v[112:113], v[116:117]
	v_pk_mul_f32 v[114:115], v[114:115], v[118:119]
	v_pk_mul_f32 v[104:105], v[104:105], v[108:109]
	v_pk_mul_f32 v[106:107], v[106:107], v[110:111]
	v_pk_mul_f32 v[96:97], v[96:97], v[100:101]
	v_pk_mul_f32 v[98:99], v[98:99], v[102:103]
	v_cvt_pk_bf16_f32 v124, v120, v121
	v_cvt_pk_bf16_f32 v125, v122, v123
	v_cvt_pk_bf16_f32 v126, v112, v113
	v_cvt_pk_bf16_f32 v127, v114, v115
	v_cvt_pk_bf16_f32 v108, v104, v105
	v_cvt_pk_bf16_f32 v109, v106, v107
	v_cvt_pk_bf16_f32 v110, v96, v97
	v_cvt_pk_bf16_f32 v111, v98, v99
	v_mov_b32_e32 v136, v132
	global_store_dwordx4 v136, v[124:127], s[8:9] sc1
	v_add_u32_e32 v137, 0x16000, v132
	global_store_dwordx4 v137, v[108:111], s[8:9] sc1
	v_pk_mul_f32 v[88:89], v[92:93], v[88:89]
	v_pk_mul_f32 v[90:91], v[94:95], v[90:91]
	v_pk_mul_f32 v[80:81], v[84:85], v[80:81]
	v_pk_mul_f32 v[82:83], v[86:87], v[82:83]
	v_pk_mul_f32 v[72:73], v[76:77], v[72:73]
	v_pk_mul_f32 v[74:75], v[78:79], v[74:75]
	v_pk_mul_f32 v[64:65], v[68:69], v[64:65]
	v_pk_mul_f32 v[66:67], v[70:71], v[66:67]
	v_pk_mul_f32 v[92:93], v[92:93], v[204:205] op_sel_hi:[1,0]
	v_pk_mul_f32 v[94:95], v[94:95], v[204:205] op_sel_hi:[1,0]
	v_pk_mul_f32 v[84:85], v[84:85], v[204:205] op_sel_hi:[1,0]
	v_pk_mul_f32 v[86:87], v[86:87], v[204:205] op_sel_hi:[1,0]
	v_pk_mul_f32 v[76:77], v[76:77], v[206:207] op_sel_hi:[1,0]
	v_pk_mul_f32 v[78:79], v[78:79], v[206:207] op_sel_hi:[1,0]
	v_pk_mul_f32 v[68:69], v[68:69], v[206:207] op_sel_hi:[1,0]
	v_pk_mul_f32 v[70:71], v[70:71], v[206:207] op_sel_hi:[1,0]
	v_exp_f32_e32 v92, v92
	v_exp_f32_e32 v93, v93
	v_exp_f32_e32 v94, v94
	v_exp_f32_e32 v95, v95
	v_exp_f32_e32 v84, v84
	v_exp_f32_e32 v85, v85
	v_exp_f32_e32 v86, v86
	v_exp_f32_e32 v87, v87
	v_exp_f32_e32 v76, v76
	v_exp_f32_e32 v77, v77
	v_exp_f32_e32 v78, v78
	v_exp_f32_e32 v79, v79
	v_exp_f32_e32 v68, v68
	v_exp_f32_e32 v69, v69
	v_exp_f32_e32 v70, v70
	v_exp_f32_e32 v71, v71
	v_pk_fma_f32 v[92:93], v[92:93], v[220:221], v[220:221] op_sel_hi:[1,0,0]
	v_pk_fma_f32 v[94:95], v[94:95], v[220:221], v[220:221] op_sel_hi:[1,0,0]
	v_pk_fma_f32 v[84:85], v[84:85], v[220:221], v[220:221] op_sel_hi:[1,0,0]
	v_pk_fma_f32 v[86:87], v[86:87], v[220:221], v[220:221] op_sel_hi:[1,0,0]
	v_pk_fma_f32 v[76:77], v[76:77], v[222:223], v[222:223] op_sel_hi:[1,0,0]
	v_pk_fma_f32 v[78:79], v[78:79], v[222:223], v[222:223] op_sel_hi:[1,0,0]
	v_pk_fma_f32 v[68:69], v[68:69], v[222:223], v[222:223] op_sel_hi:[1,0,0]
	v_pk_fma_f32 v[70:71], v[70:71], v[222:223], v[222:223] op_sel_hi:[1,0,0]
	v_rcp_f32_e32 v92, v92
	v_rcp_f32_e32 v93, v93
	v_rcp_f32_e32 v94, v94
	v_rcp_f32_e32 v95, v95
	v_rcp_f32_e32 v84, v84
	v_rcp_f32_e32 v85, v85
	v_rcp_f32_e32 v86, v86
	v_rcp_f32_e32 v87, v87
	v_rcp_f32_e32 v76, v76
	v_rcp_f32_e32 v77, v77
	v_rcp_f32_e32 v78, v78
	v_rcp_f32_e32 v79, v79
	v_rcp_f32_e32 v68, v68
	v_rcp_f32_e32 v69, v69
	v_rcp_f32_e32 v70, v70
	v_rcp_f32_e32 v71, v71
	v_pk_mul_f32 v[88:89], v[88:89], v[92:93]
	v_pk_mul_f32 v[90:91], v[90:91], v[94:95]
	v_pk_mul_f32 v[80:81], v[80:81], v[84:85]
	v_pk_mul_f32 v[82:83], v[82:83], v[86:87]
	v_pk_mul_f32 v[72:73], v[72:73], v[76:77]
	v_pk_mul_f32 v[74:75], v[74:75], v[78:79]
	v_pk_mul_f32 v[64:65], v[64:65], v[68:69]
	v_pk_mul_f32 v[66:67], v[66:67], v[70:71]
	v_cvt_pk_bf16_f32 v92, v88, v89
	v_cvt_pk_bf16_f32 v93, v90, v91
	v_cvt_pk_bf16_f32 v94, v80, v81
	v_cvt_pk_bf16_f32 v95, v82, v83
	v_cvt_pk_bf16_f32 v76, v72, v73
	v_cvt_pk_bf16_f32 v77, v74, v75
	v_cvt_pk_bf16_f32 v78, v64, v65
	v_cvt_pk_bf16_f32 v79, v66, v67
	v_add_u32_e32 v138, 0x2c000, v132
	global_store_dwordx4 v138, v[92:95], s[8:9] sc1
	v_add_u32_e32 v139, 0x42000, v132
	global_store_dwordx4 v139, v[76:79], s[8:9] sc1
	s_and_b64 vcc, exec, s[42:43]
	s_cbranch_vccz .LBB0_1652
	s_barrier
; #define PG8_BAR __builtin_amdgcn_s_barrier()
; __device__ __forceinline__ unsigned pk2(float lo, float hi) { return pg8::cvt_pk_bf16(lo, hi); }
; __device__ __forceinline__ float siluf_(float x) { return x * sigmoidf_(x); }
; template <class Epi, class Sched, bool ALIGN_EPI = false, bool SP2 = false>
; __device__ __forceinline__ void gemm_phase(PG8_LAS unsigned char* lds, const Gemm g, const Sched& S, const Epi& E) {
;     ...
;         if constexpr (!Epi::AFTER_DRAIN) { E(acc, cur, wr, wc, fr, fq); S.done(cur); }
;         if (!has_next) break;
;         { typename Epi::Pre pren = E.issue(nxt, wr, wc, fr, fq); E.finish(acc, pren); }
;         cur = nxt; cA = nA; cB = nB; ++ui;
;         if constexpr (ALIGN_EPI) { if (wr == 1) PG8_BAR; }
;     __device__ __forceinline__ void operator()(const f32x4 (&acc)[2][2][4][2], const pg8::Unit& u, int wr, int wc, int fr, int fq) const {
;     ...
;         for (int ai = 0; ai < 2; ++ai)
; #pragma unroll
;             for (int m = 0; m < 4; ++m) {
;                 const int row = row0 + ai * 128 + m * 16; const float r = rs[ai * 4 + m];
;                 float h[8];
; #pragma unroll
;                 for (int n = 0; n < 2; ++n)
; #pragma unroll
;                     for (int j = 0; j < 4; ++j) { const float g = acc[ai][0][m][n][j] * r, up = acc[ai][1][m][n][j] * r; h[n * 4 + j] = siluf_(g) * up; }
;                 u32x4 w; w.x = pk2(h[0], h[1]); w.y = pk2(h[2], h[3]); w.z = pk2(h[4], h[5]); w.w = pk2(h[6], h[7]);
;                 *(u32x4*)(H + (size_t)row * FF + col0) = w;
;             }
.LBB0_1652:
	v_pk_mul_f32 v[56:57], v[60:61], v[56:57]
	v_pk_mul_f32 v[58:59], v[62:63], v[58:59]
	v_pk_mul_f32 v[48:49], v[52:53], v[48:49]
	v_pk_mul_f32 v[50:51], v[54:55], v[50:51]
	v_pk_mul_f32 v[40:41], v[44:45], v[40:41]
	v_pk_mul_f32 v[42:43], v[46:47], v[42:43]
	v_pk_mul_f32 v[32:33], v[36:37], v[32:33]
	v_pk_mul_f32 v[34:35], v[38:39], v[34:35]
	v_pk_mul_f32 v[60:61], v[60:61], v[208:209] op_sel_hi:[1,0]
	v_pk_mul_f32 v[62:63], v[62:63], v[208:209] op_sel_hi:[1,0]
	v_pk_mul_f32 v[52:53], v[52:53], v[208:209] op_sel_hi:[1,0]
	v_pk_mul_f32 v[54:55], v[54:55], v[208:209] op_sel_hi:[1,0]
	v_pk_mul_f32 v[44:45], v[44:45], v[210:211] op_sel_hi:[1,0]
	v_pk_mul_f32 v[46:47], v[46:47], v[210:211] op_sel_hi:[1,0]
	v_pk_mul_f32 v[36:37], v[36:37], v[210:211] op_sel_hi:[1,0]
	v_pk_mul_f32 v[38:39], v[38:39], v[210:211] op_sel_hi:[1,0]
	v_exp_f32_e32 v60, v60
	v_exp_f32_e32 v61, v61
	v_exp_f32_e32 v62, v62
	v_exp_f32_e32 v63, v63
	v_exp_f32_e32 v52, v52
	v_exp_f32_e32 v53, v53
	v_exp_f32_e32 v54, v54
	v_exp_f32_e32 v55, v55
	v_exp_f32_e32 v44, v44
	v_exp_f32_e32 v45, v45
	v_exp_f32_e32 v46, v46
	v_exp_f32_e32 v47, v47
	v_exp_f32_e32 v36, v36
	v_exp_f32_e32 v37, v37
	v_exp_f32_e32 v38, v38
	v_exp_f32_e32 v39, v39
	v_pk_fma_f32 v[60:61], v[60:61], v[224:225], v[224:225] op_sel_hi:[1,0,0]
	v_pk_fma_f32 v[62:63], v[62:63], v[224:225], v[224:225] op_sel_hi:[1,0,0]
	v_pk_fma_f32 v[52:53], v[52:53], v[224:225], v[224:225] op_sel_hi:[1,0,0]
	v_pk_fma_f32 v[54:55], v[54:55], v[224:225], v[224:225] op_sel_hi:[1,0,0]
	v_pk_fma_f32 v[44:45], v[44:45], v[226:227], v[226:227] op_sel_hi:[1,0,0]
	v_pk_fma_f32 v[46:47], v[46:47], v[226:227], v[226:227] op_sel_hi:[1,0,0]
	v_pk_fma_f32 v[36:37], v[36:37], v[226:227], v[226:227] op_sel_hi:[1,0,0]
	v_pk_fma_f32 v[38:39], v[38:39], v[226:227], v[226:227] op_sel_hi:[1,0,0]
	v_rcp_f32_e32 v60, v60
	v_rcp_f32_e32 v61, v61
	v_rcp_f32_e32 v62, v62
	v_rcp_f32_e32 v63, v63
	v_rcp_f32_e32 v52, v52
	v_rcp_f32_e32 v53, v53
	v_rcp_f32_e32 v54, v54
	v_rcp_f32_e32 v55, v55
	v_rcp_f32_e32 v44, v44
	v_rcp_f32_e32 v45, v45
	v_rcp_f32_e32 v46, v46
	v_rcp_f32_e32 v47, v47
	v_rcp_f32_e32 v36, v36
	v_rcp_f32_e32 v37, v37
	v_rcp_f32_e32 v38, v38
	v_rcp_f32_e32 v39, v39
	v_pk_mul_f32 v[56:57], v[56:57], v[60:61]
	v_pk_mul_f32 v[58:59], v[58:59], v[62:63]
	v_pk_mul_f32 v[48:49], v[48:49], v[52:53]
	v_pk_mul_f32 v[50:51], v[50:51], v[54:55]
	v_pk_mul_f32 v[40:41], v[40:41], v[44:45]
	v_pk_mul_f32 v[42:43], v[42:43], v[46:47]
	v_pk_mul_f32 v[32:33], v[32:33], v[36:37]
	v_pk_mul_f32 v[34:35], v[34:35], v[38:39]
	v_cvt_pk_bf16_f32 v60, v56, v57
	v_cvt_pk_bf16_f32 v61, v58, v59
	v_cvt_pk_bf16_f32 v62, v48, v49
	v_cvt_pk_bf16_f32 v63, v50, v51
	v_cvt_pk_bf16_f32 v44, v40, v41
	v_cvt_pk_bf16_f32 v45, v42, v43
	v_cvt_pk_bf16_f32 v46, v32, v33
	v_cvt_pk_bf16_f32 v47, v34, v35
	v_add_u32_e32 v140, 0xb0000, v132
	global_store_dwordx4 v140, v[60:63], s[8:9] sc1
	v_add_u32_e32 v141, 0xc6000, v132
	global_store_dwordx4 v141, v[44:47], s[8:9] sc1
	v_pk_mul_f32 v[24:25], v[28:29], v[24:25]
	v_pk_mul_f32 v[26:27], v[30:31], v[26:27]
	v_pk_mul_f32 v[16:17], v[20:21], v[16:17]
	v_pk_mul_f32 v[18:19], v[22:23], v[18:19]
	v_pk_mul_f32 v[8:9], v[12:13], v[8:9]
	v_pk_mul_f32 v[10:11], v[14:15], v[10:11]
	v_pk_mul_f32 v[0:1], v[4:5], v[0:1]
	v_pk_mul_f32 v[2:3], v[6:7], v[2:3]
	v_pk_mul_f32 v[28:29], v[28:29], v[212:213] op_sel_hi:[1,0]
	v_pk_mul_f32 v[30:31], v[30:31], v[212:213] op_sel_hi:[1,0]
	v_pk_mul_f32 v[20:21], v[20:21], v[212:213] op_sel_hi:[1,0]
	v_pk_mul_f32 v[22:23], v[22:23], v[212:213] op_sel_hi:[1,0]
	v_pk_mul_f32 v[12:13], v[12:13], v[214:215] op_sel_hi:[1,0]
	v_pk_mul_f32 v[14:15], v[14:15], v[214:215] op_sel_hi:[1,0]
	v_pk_mul_f32 v[4:5], v[4:5], v[214:215] op_sel_hi:[1,0]
	v_pk_mul_f32 v[6:7], v[6:7], v[214:215] op_sel_hi:[1,0]
	v_exp_f32_e32 v28, v28
	v_exp_f32_e32 v29, v29
	v_exp_f32_e32 v30, v30
	v_exp_f32_e32 v31, v31
	v_exp_f32_e32 v20, v20
	v_exp_f32_e32 v21, v21
	v_exp_f32_e32 v22, v22
	v_exp_f32_e32 v23, v23
	v_exp_f32_e32 v12, v12
	v_exp_f32_e32 v13, v13
	v_exp_f32_e32 v14, v14
	v_exp_f32_e32 v15, v15
	v_exp_f32_e32 v4, v4
	v_exp_f32_e32 v5, v5
	v_exp_f32_e32 v6, v6
	v_exp_f32_e32 v7, v7
	v_pk_fma_f32 v[28:29], v[28:29], v[228:229], v[228:229] op_sel_hi:[1,0,0]
	v_pk_fma_f32 v[30:31], v[30:31], v[228:229], v[228:229] op_sel_hi:[1,0,0]
	v_pk_fma_f32 v[20:21], v[20:21], v[228:229], v[228:229] op_sel_hi:[1,0,0]
	v_pk_fma_f32 v[22:23], v[22:23], v[228:229], v[228:229] op_sel_hi:[1,0,0]
	v_pk_fma_f32 v[12:13], v[12:13], v[230:231], v[230:231] op_sel_hi:[1,0,0]
	v_pk_fma_f32 v[14:15], v[14:15], v[230:231], v[230:231] op_sel_hi:[1,0,0]
	v_pk_fma_f32 v[4:5], v[4:5], v[230:231], v[230:231] op_sel_hi:[1,0,0]
	v_pk_fma_f32 v[6:7], v[6:7], v[230:231], v[230:231] op_sel_hi:[1,0,0]
	v_rcp_f32_e32 v28, v28
	v_rcp_f32_e32 v29, v29
	v_rcp_f32_e32 v30, v30
	v_rcp_f32_e32 v31, v31
	v_rcp_f32_e32 v20, v20
	v_rcp_f32_e32 v21, v21
	v_rcp_f32_e32 v22, v22
	v_rcp_f32_e32 v23, v23
	v_rcp_f32_e32 v12, v12
	v_rcp_f32_e32 v13, v13
	v_rcp_f32_e32 v14, v14
	v_rcp_f32_e32 v15, v15
	v_rcp_f32_e32 v4, v4
	v_rcp_f32_e32 v5, v5
	v_rcp_f32_e32 v6, v6
	v_rcp_f32_e32 v7, v7
	v_pk_mul_f32 v[24:25], v[24:25], v[28:29]
	v_pk_mul_f32 v[26:27], v[26:27], v[30:31]
	v_pk_mul_f32 v[16:17], v[16:17], v[20:21]
	v_pk_mul_f32 v[18:19], v[18:19], v[22:23]
	v_pk_mul_f32 v[8:9], v[8:9], v[12:13]
	v_pk_mul_f32 v[10:11], v[10:11], v[14:15]
	v_pk_mul_f32 v[0:1], v[0:1], v[4:5]
	v_pk_mul_f32 v[2:3], v[2:3], v[6:7]
	v_cvt_pk_bf16_f32 v28, v24, v25
	v_cvt_pk_bf16_f32 v29, v26, v27
	v_cvt_pk_bf16_f32 v30, v16, v17
	v_cvt_pk_bf16_f32 v31, v18, v19
	v_cvt_pk_bf16_f32 v12, v8, v9
	v_cvt_pk_bf16_f32 v13, v10, v11
	v_cvt_pk_bf16_f32 v14, v0, v1
	v_cvt_pk_bf16_f32 v15, v2, v3
	v_add_u32_e32 v142, 0xdc000, v132
	global_store_dwordx4 v142, v[28:31], s[8:9] sc1
	v_add_u32_e32 v143, 0xf2000, v132
	global_store_dwordx4 v143, v[12:15], s[8:9] sc1
	s_andn2_b64 vcc, exec, s[36:37]
	s_mov_b64 s[0:1], -1
	s_cbranch_vccnz .LBB0_1643
	s_andn2_b64 vcc, exec, s[40:41]
	s_cbranch_vccnz .LBB0_1642
	s_barrier
	s_branch .LBB0_1642
